# k14: k13 + split-K consumer streams the second group of partial-tile loads (issued as each register quad is consumed)
# speedup vs baseline: 1.0054x; 1.0036x over previous
; __device__ __forceinline__ void slab_accumulate(f32x4 (&acc)[2][2][4][2], float* slab, unsigned* fl, int nsl, int wr, int wc, int fr, int fq) {
;     ...
;     for (int s = 0; s < nsl; ++s) {
;         const __amdgpu_buffer_rsrc_t rs_ = __builtin_amdgcn_make_buffer_rsrc((void*)(slab + (size_t)s * 65536), 0, 262144, 0x00020000);
; #pragma unroll
;         for (int ai = 0; ai < 2; ++ai) {
;             u32x4 t_[2][4][2];
; #pragma unroll
;             for (int bj = 0; bj < 2; ++bj)
; #pragma unroll
;                 for (int m = 0; m < 4; ++m)
; #pragma unroll
;                     for (int n = 0; n < 2; ++n) t_[bj][m][n] = __builtin_amdgcn_raw_buffer_load_b128(rs_, vo_, (((ai * 2 + bj) * 4 + m) * 2 + n) * 8192, 16);
; #pragma unroll
;             for (int bj = 0; bj < 2; ++bj)
; #pragma unroll
;                 for (int m = 0; m < 4; ++m)
; #pragma unroll
;                     for (int n = 0; n < 2; ++n) acc[ai][bj][m][n] = acc[ai][bj][m][n] + __builtin_bit_cast(f32x4, t_[bj][m][n]);
;             asm volatile("" ::: "memory");
;         }
;     }
.LBB0_243:
	s_add_u32 s84, s8, s6
	s_addc_u32 s10, s9, s7
	s_and_b32 s85, s10, 0xffff
	s_mov_b32 s87, s71
	buffer_load_dwordx4 v[132:135], v0, s[84:87], 0 offen sc1
	buffer_load_dwordx4 v[136:139], v0, s[84:87], s2 offen sc1
	buffer_load_dwordx4 v[142:145], v0, s[84:87], s11 offen sc1
	buffer_load_dwordx4 v[146:149], v0, s[84:87], s22 offen sc1
	buffer_load_dwordx4 v[152:155], v0, s[84:87], s27 offen sc1
	buffer_load_dwordx4 v[156:159], v0, s[84:87], s28 offen sc1
	buffer_load_dwordx4 v[160:163], v0, s[84:87], s36 offen sc1
	buffer_load_dwordx4 v[164:167], v0, s[84:87], s37 offen sc1
	buffer_load_dwordx4 v[168:171], v0, s[84:87], s62 offen sc1
	buffer_load_dwordx4 v[172:175], v0, s[84:87], s15 offen sc1
	buffer_load_dwordx4 v[176:179], v0, s[84:87], s20 offen sc1
	buffer_load_dwordx4 v[180:183], v0, s[84:87], s21 offen sc1
	buffer_load_dwordx4 v[184:187], v0, s[84:87], s23 offen sc1
	buffer_load_dwordx4 v[188:191], v0, s[84:87], s25 offen sc1
	buffer_load_dwordx4 v[192:195], v0, s[84:87], s29 offen sc1
	buffer_load_dwordx4 v[196:199], v0, s[84:87], s35 offen sc1
	s_add_u32 s6, s6, 0x40000
	s_addc_u32 s7, s7, 0
	s_cmp_lg_u32 s6, 0xc0000
	s_waitcnt vmcnt(15)
	v_pk_add_f32 v[130:131], v[130:131], v[134:135]
	v_pk_add_f32 v[128:129], v[128:129], v[132:133]
	buffer_load_dwordx4 v[132:135], v0, s[84:87], s71 offen sc1
	s_waitcnt vmcnt(15)
	v_pk_add_f32 v[126:127], v[126:127], v[138:139]
	v_pk_add_f32 v[124:125], v[124:125], v[136:137]
	buffer_load_dwordx4 v[136:139], v0, s[84:87], s38 offen sc1
	s_waitcnt vmcnt(15)
	v_pk_add_f32 v[114:115], v[114:115], v[144:145]
	v_pk_add_f32 v[112:113], v[112:113], v[142:143]
	buffer_load_dwordx4 v[142:145], v0, s[84:87], s40 offen sc1
	s_waitcnt vmcnt(15)
	v_pk_add_f32 v[110:111], v[110:111], v[148:149]
	v_pk_add_f32 v[108:109], v[108:109], v[146:147]
	buffer_load_dwordx4 v[146:149], v0, s[84:87], s41 offen sc1
	s_waitcnt vmcnt(15)
	v_pk_add_f32 v[98:99], v[98:99], v[154:155]
	v_pk_add_f32 v[96:97], v[96:97], v[152:153]
	buffer_load_dwordx4 v[152:155], v0, s[84:87], s43 offen sc1
	s_waitcnt vmcnt(15)
	v_pk_add_f32 v[94:95], v[94:95], v[158:159]
	v_pk_add_f32 v[92:93], v[92:93], v[156:157]
	buffer_load_dwordx4 v[156:159], v0, s[84:87], s44 offen sc1
	s_waitcnt vmcnt(15)
	v_pk_add_f32 v[82:83], v[82:83], v[162:163]
	v_pk_add_f32 v[80:81], v[80:81], v[160:161]
	buffer_load_dwordx4 v[160:163], v0, s[84:87], s45 offen sc1
	s_waitcnt vmcnt(15)
	v_pk_add_f32 v[78:79], v[78:79], v[166:167]
	v_pk_add_f32 v[76:77], v[76:77], v[164:165]
	buffer_load_dwordx4 v[164:167], v0, s[84:87], s49 offen sc1
	s_waitcnt vmcnt(15)
	v_pk_add_f32 v[122:123], v[122:123], v[170:171]
	v_pk_add_f32 v[120:121], v[120:121], v[168:169]
	buffer_load_dwordx4 v[168:171], v0, s[84:87], s50 offen sc1
	s_waitcnt vmcnt(15)
	v_pk_add_f32 v[118:119], v[118:119], v[174:175]
	v_pk_add_f32 v[116:117], v[116:117], v[172:173]
	buffer_load_dwordx4 v[172:175], v0, s[84:87], s51 offen sc1
	s_waitcnt vmcnt(15)
	v_pk_add_f32 v[106:107], v[106:107], v[178:179]
	v_pk_add_f32 v[104:105], v[104:105], v[176:177]
	buffer_load_dwordx4 v[176:179], v0, s[84:87], s56 offen sc1
	s_waitcnt vmcnt(15)
	v_pk_add_f32 v[102:103], v[102:103], v[182:183]
	v_pk_add_f32 v[100:101], v[100:101], v[180:181]
	buffer_load_dwordx4 v[180:183], v0, s[84:87], s57 offen sc1
	s_waitcnt vmcnt(15)
	v_pk_add_f32 v[90:91], v[90:91], v[186:187]
	v_pk_add_f32 v[88:89], v[88:89], v[184:185]
	buffer_load_dwordx4 v[184:187], v0, s[84:87], s58 offen sc1
	s_waitcnt vmcnt(15)
	v_pk_add_f32 v[86:87], v[86:87], v[190:191]
	v_pk_add_f32 v[84:85], v[84:85], v[188:189]
	buffer_load_dwordx4 v[188:191], v0, s[84:87], s59 offen sc1
	s_waitcnt vmcnt(15)
	v_pk_add_f32 v[74:75], v[74:75], v[194:195]
	v_pk_add_f32 v[72:73], v[72:73], v[192:193]
	buffer_load_dwordx4 v[192:195], v0, s[84:87], s67 offen sc1
	s_waitcnt vmcnt(15)
	v_pk_add_f32 v[70:71], v[70:71], v[198:199]
	v_pk_add_f32 v[68:69], v[68:69], v[196:197]
	buffer_load_dwordx4 v[196:199], v0, s[84:87], s68 offen sc1
	s_waitcnt vmcnt(15)
	v_pk_add_f32 v[66:67], v[66:67], v[134:135]
	v_pk_add_f32 v[64:65], v[64:65], v[132:133]
	s_waitcnt vmcnt(14)
	v_pk_add_f32 v[62:63], v[62:63], v[138:139]
	v_pk_add_f32 v[60:61], v[60:61], v[136:137]
	s_waitcnt vmcnt(13)
	v_pk_add_f32 v[50:51], v[50:51], v[144:145]
	v_pk_add_f32 v[48:49], v[48:49], v[142:143]
	s_waitcnt vmcnt(12)
	v_pk_add_f32 v[46:47], v[46:47], v[148:149]
	v_pk_add_f32 v[44:45], v[44:45], v[146:147]
	s_waitcnt vmcnt(11)
	v_pk_add_f32 v[34:35], v[34:35], v[154:155]
	v_pk_add_f32 v[32:33], v[32:33], v[152:153]
	s_waitcnt vmcnt(10)
	v_pk_add_f32 v[30:31], v[30:31], v[158:159]
	v_pk_add_f32 v[28:29], v[28:29], v[156:157]
	s_waitcnt vmcnt(9)
	v_pk_add_f32 v[18:19], v[18:19], v[162:163]
	v_pk_add_f32 v[16:17], v[16:17], v[160:161]
	s_waitcnt vmcnt(8)
	v_pk_add_f32 v[14:15], v[14:15], v[166:167]
	v_pk_add_f32 v[12:13], v[12:13], v[164:165]
	s_waitcnt vmcnt(7)
	v_pk_add_f32 v[58:59], v[58:59], v[170:171]
	v_pk_add_f32 v[56:57], v[56:57], v[168:169]
	s_waitcnt vmcnt(6)
	v_pk_add_f32 v[54:55], v[54:55], v[174:175]
	v_pk_add_f32 v[52:53], v[52:53], v[172:173]
	s_waitcnt vmcnt(5)
	v_pk_add_f32 v[42:43], v[42:43], v[178:179]
	v_pk_add_f32 v[40:41], v[40:41], v[176:177]
	s_waitcnt vmcnt(4)
	v_pk_add_f32 v[38:39], v[38:39], v[182:183]
	v_pk_add_f32 v[36:37], v[36:37], v[180:181]
	s_waitcnt vmcnt(3)
	v_pk_add_f32 v[26:27], v[26:27], v[186:187]
	v_pk_add_f32 v[24:25], v[24:25], v[184:185]
	s_waitcnt vmcnt(2)
	v_pk_add_f32 v[22:23], v[22:23], v[190:191]
	v_pk_add_f32 v[20:21], v[20:21], v[188:189]
	s_waitcnt vmcnt(1)
	v_pk_add_f32 v[10:11], v[10:11], v[194:195]
	v_pk_add_f32 v[8:9], v[8:9], v[192:193]
	s_waitcnt vmcnt(0)
	v_pk_add_f32 v[6:7], v[6:7], v[198:199]
	v_pk_add_f32 v[4:5], v[4:5], v[196:197]
	s_cbranch_scc1 .LBB0_243
; __device__ __forceinline__ unsigned cvt_pk_bf16(float lo, float hi) { unsigned r; asm volatile("v_cvt_pk_bf16_f32 %0, %1, %2" : "=v"(r) : "v"(lo), "v"(hi)); return r; }
;     __device__ __forceinline__ void operator()(f32x4 (&acc)[2][2][4][2], const Unit& u, int wr, int wc, int fr, int fq) const {
;     ...
;                     u32x4 t[2][2];
; #pragma unroll
;                     for (int mm = 0; mm < 2; ++mm) { const bf16_t* rowp = XB + (size_t)(row0 + ai * HALF + (2 * mp + mm) * 16) * ldc + col0;
; #pragma unroll
;                         for (int bj = 0; bj < 2; ++bj) t[mm][bj] = *(const u32x4*)(rowp + bj * HALF); }
; #pragma unroll
;                     for (int mm = 0; mm < 2; ++mm)
; #pragma unroll
;                         for (int bj = 0; bj < 2; ++bj) { const u32x4 w = t[mm][bj];
;                             acc[ai][bj][2 * mp + mm][0] = acc[ai][bj][2 * mp + mm][0] + (f32x4){__builtin_bit_cast(float, w.x << 16), __builtin_bit_cast(float, w.x & 0xffff0000u), __builtin_bit_cast(float, w.y << 16), __builtin_bit_cast(float, w.y & 0xffff0000u)};
;                             acc[ai][bj][2 * mp + mm][1] = acc[ai][bj][2 * mp + mm][1] + (f32x4){__builtin_bit_cast(float, w.z << 16), __builtin_bit_cast(float, w.z & 0xffff0000u), __builtin_bit_cast(float, w.w << 16), __builtin_bit_cast(float, w.w & 0xffff0000u)}; }
;                 }
; #pragma unroll
;                 for (int mm = 0; mm < 2; ++mm) { const int m = 2 * mp + mm; const int row = row0 + ai * HALF + m * 16; float sq = 0.f;
; #pragma unroll
;                     for (int bj = 0; bj < 2; ++bj) { const f32x4 v0 = acc[ai][bj][m][0], v1 = acc[ai][bj][m][1];
;                         sq += ((v0[0] * v0[0] + v0[1] * v0[1]) + (v0[2] * v0[2] + v0[3] * v0[3])) + ((v1[0] * v1[0] + v1[1] * v1[1]) + (v1[2] * v1[2] + v1[3] * v1[3]));
;                         if (!Y) { u32x4 w; w.x = cvt_pk_bf16(v0[0], v0[1]); w.y = cvt_pk_bf16(v0[2], v0[3]); w.z = cvt_pk_bf16(v1[0], v1[1]); w.w = cvt_pk_bf16(v1[2], v1[3]);
;                             *(u32x4*)(XB + (size_t)row * ldc + col0 + bj * HALF) = w; } }
	v_lshlrev_b32_e32 v0, 3, v150
	v_lshl_or_b32 v0, s24, 5, v0
	v_lshl_add_u32 v144, s19, 8, v140
	v_lshl_or_b32 v0, s26, 8, v0
	v_ashrrev_i32_e32 v1, 31, v0
	v_ashrrev_i32_e32 v145, 31, v144
	v_lshl_add_u64 v[158:159], v[0:1], 1, s[74:75]
	v_lshlrev_b64 v[148:149], 11, v[144:145]
	v_or_b32_e32 v146, 16, v144
	v_lshl_add_u64 v[132:133], v[158:159], 0, v[148:149]
	v_ashrrev_i32_e32 v147, 31, v146
	global_load_dwordx4 v[154:157], v[132:133], off
	global_load_dwordx4 v[140:143], v[132:133], off offset:256
	v_lshlrev_b64 v[152:153], 11, v[146:147]
	v_lshl_add_u64 v[132:133], v[158:159], 0, v[152:153]
	global_load_dwordx4 v[136:139], v[132:133], off
	s_nop 0
	global_load_dwordx4 v[132:135], v[132:133], off offset:256
	s_cmp_eq_u64 s[0:1], 0
	s_cselect_b64 s[8:9], -1, 0
	s_cmp_lg_u64 s[0:1], 0
	s_cselect_b64 s[10:11], -1, 0
	s_movk_i32 s2, 0x2000
	s_and_b64 vcc, exec, s[10:11]
	s_waitcnt vmcnt(3)
	v_lshlrev_b32_e32 v160, 16, v154
	v_and_b32_e32 v161, 0xffff0000, v154
	v_lshlrev_b32_e32 v154, 16, v155
	v_and_b32_e32 v155, 0xffff0000, v155
	v_pk_add_f32 v[130:131], v[130:131], v[154:155]
	v_lshlrev_b32_e32 v154, 16, v156
	v_and_b32_e32 v155, 0xffff0000, v156
	v_lshlrev_b32_e32 v156, 16, v157
	v_and_b32_e32 v157, 0xffff0000, v157
	v_pk_add_f32 v[128:129], v[128:129], v[160:161]
	v_pk_add_f32 v[126:127], v[126:127], v[156:157]
	v_pk_add_f32 v[124:125], v[124:125], v[154:155]
	s_cbranch_vccnz .LBB0_246
	v_lshl_add_u64 v[160:161], s[74:75], 0, v[148:149]
	v_lshl_add_u64 v[160:161], v[0:1], 1, v[160:161]
	v_cvt_pk_bf16_f32 v154, v128, v129
	v_cvt_pk_bf16_f32 v155, v130, v131
	v_cvt_pk_bf16_f32 v156, v124, v125
	v_cvt_pk_bf16_f32 v157, v126, v127
	global_store_dwordx4 v[160:161], v[154:157], off

; __device__ __forceinline__ void slab_accumulate(f32x4 (&acc)[2][2][4][2], float* slab, unsigned* fl, int nsl, int wr, int wc, int fr, int fq) {
;     ...
;     for (int s = 0; s < nsl; ++s) {
;         const __amdgpu_buffer_rsrc_t rs_ = __builtin_amdgcn_make_buffer_rsrc((void*)(slab + (size_t)s * 65536), 0, 262144, 0x00020000);
; #pragma unroll
;         for (int ai = 0; ai < 2; ++ai) {
;             u32x4 t_[2][4][2];
; #pragma unroll
;             for (int bj = 0; bj < 2; ++bj)
; #pragma unroll
;                 for (int m = 0; m < 4; ++m)
; #pragma unroll
;                     for (int n = 0; n < 2; ++n) t_[bj][m][n] = __builtin_amdgcn_raw_buffer_load_b128(rs_, vo_, (((ai * 2 + bj) * 4 + m) * 2 + n) * 8192, 16);
; #pragma unroll
;             for (int bj = 0; bj < 2; ++bj)
; #pragma unroll
;                 for (int m = 0; m < 4; ++m)
; #pragma unroll
;                     for (int n = 0; n < 2; ++n) acc[ai][bj][m][n] = acc[ai][bj][m][n] + __builtin_bit_cast(f32x4, t_[bj][m][n]);
;             asm volatile("" ::: "memory");
;         }
;     }
.LBB0_647:
	s_add_u32 s84, s7, s4
	s_addc_u32 s12, s9, s5
	s_and_b32 s85, s12, 0xffff
	s_mov_b32 s87, s71
	buffer_load_dwordx4 v[132:135], v0, s[84:87], 0 offen sc1
	buffer_load_dwordx4 v[138:141], v0, s[84:87], s2 offen sc1
	buffer_load_dwordx4 v[142:145], v0, s[84:87], s16 offen sc1
	buffer_load_dwordx4 v[146:149], v0, s[84:87], s20 offen sc1
	buffer_load_dwordx4 v[150:153], v0, s[84:87], s23 offen sc1
	buffer_load_dwordx4 v[154:157], v0, s[84:87], s24 offen sc1
	buffer_load_dwordx4 v[158:161], v0, s[84:87], s27 offen sc1
	buffer_load_dwordx4 v[162:165], v0, s[84:87], s28 offen sc1
	buffer_load_dwordx4 v[166:169], v0, s[84:87], s50 offen sc1
	buffer_load_dwordx4 v[170:173], v0, s[84:87], s17 offen sc1
	buffer_load_dwordx4 v[174:177], v0, s[84:87], s18 offen sc1
	buffer_load_dwordx4 v[178:181], v0, s[84:87], s19 offen sc1
	buffer_load_dwordx4 v[182:185], v0, s[84:87], s21 offen sc1
	buffer_load_dwordx4 v[186:189], v0, s[84:87], s22 offen sc1
	buffer_load_dwordx4 v[190:193], v0, s[84:87], s25 offen sc1
	buffer_load_dwordx4 v[194:197], v0, s[84:87], s26 offen sc1
	s_add_u32 s4, s4, 0x40000
	s_addc_u32 s5, s5, 0
	s_cmp_lg_u32 s4, 0xc0000
	s_waitcnt vmcnt(15)
	v_pk_add_f32 v[130:131], v[130:131], v[134:135]
	v_pk_add_f32 v[128:129], v[128:129], v[132:133]
	buffer_load_dwordx4 v[132:135], v0, s[84:87], s71 offen sc1
	s_waitcnt vmcnt(15)
	v_pk_add_f32 v[126:127], v[126:127], v[140:141]
	v_pk_add_f32 v[124:125], v[124:125], v[138:139]
	buffer_load_dwordx4 v[138:141], v0, s[84:87], s29 offen sc1
	s_waitcnt vmcnt(15)
	v_pk_add_f32 v[114:115], v[114:115], v[144:145]
	v_pk_add_f32 v[112:113], v[112:113], v[142:143]
	buffer_load_dwordx4 v[142:145], v0, s[84:87], s35 offen sc1
	s_waitcnt vmcnt(15)
	v_pk_add_f32 v[110:111], v[110:111], v[148:149]
	v_pk_add_f32 v[108:109], v[108:109], v[146:147]
	buffer_load_dwordx4 v[146:149], v0, s[84:87], s38 offen sc1
	s_waitcnt vmcnt(15)
	v_pk_add_f32 v[98:99], v[98:99], v[152:153]
	v_pk_add_f32 v[96:97], v[96:97], v[150:151]
	buffer_load_dwordx4 v[150:153], v0, s[84:87], s43 offen sc1
	s_waitcnt vmcnt(15)
	v_pk_add_f32 v[94:95], v[94:95], v[156:157]
	v_pk_add_f32 v[92:93], v[92:93], v[154:155]
	buffer_load_dwordx4 v[154:157], v0, s[84:87], s44 offen sc1
	s_waitcnt vmcnt(15)
	v_pk_add_f32 v[82:83], v[82:83], v[160:161]
	v_pk_add_f32 v[80:81], v[80:81], v[158:159]
	buffer_load_dwordx4 v[158:161], v0, s[84:87], s45 offen sc1
	s_waitcnt vmcnt(15)
	v_pk_add_f32 v[78:79], v[78:79], v[164:165]
	v_pk_add_f32 v[76:77], v[76:77], v[162:163]
	buffer_load_dwordx4 v[162:165], v0, s[84:87], s46 offen sc1
	s_waitcnt vmcnt(15)
	v_pk_add_f32 v[122:123], v[122:123], v[168:169]
	v_pk_add_f32 v[120:121], v[120:121], v[166:167]
	buffer_load_dwordx4 v[166:169], v0, s[84:87], s47 offen sc1
	s_waitcnt vmcnt(15)
	v_pk_add_f32 v[118:119], v[118:119], v[172:173]
	v_pk_add_f32 v[116:117], v[116:117], v[170:171]
	buffer_load_dwordx4 v[170:173], v0, s[84:87], s13 offen sc1
	s_waitcnt vmcnt(15)
	v_pk_add_f32 v[106:107], v[106:107], v[176:177]
	v_pk_add_f32 v[104:105], v[104:105], v[174:175]
	buffer_load_dwordx4 v[174:177], v0, s[84:87], s14 offen sc1
	s_waitcnt vmcnt(15)
	v_pk_add_f32 v[102:103], v[102:103], v[180:181]
	v_pk_add_f32 v[100:101], v[100:101], v[178:179]
	buffer_load_dwordx4 v[178:181], v0, s[84:87], s15 offen sc1
	s_waitcnt vmcnt(15)
	v_pk_add_f32 v[90:91], v[90:91], v[184:185]
	v_pk_add_f32 v[88:89], v[88:89], v[182:183]
	buffer_load_dwordx4 v[182:185], v0, s[84:87], s34 offen sc1
	s_waitcnt vmcnt(15)
	v_pk_add_f32 v[86:87], v[86:87], v[188:189]
	v_pk_add_f32 v[84:85], v[84:85], v[186:187]
	buffer_load_dwordx4 v[186:189], v0, s[84:87], s40 offen sc1
	s_waitcnt vmcnt(15)
	v_pk_add_f32 v[74:75], v[74:75], v[192:193]
	v_pk_add_f32 v[72:73], v[72:73], v[190:191]
	buffer_load_dwordx4 v[190:193], v0, s[84:87], s41 offen sc1
	s_waitcnt vmcnt(15)
	v_pk_add_f32 v[70:71], v[70:71], v[196:197]
	v_pk_add_f32 v[68:69], v[68:69], v[194:195]
	buffer_load_dwordx4 v[194:197], v0, s[84:87], s49 offen sc1
	s_waitcnt vmcnt(15)
	v_pk_add_f32 v[66:67], v[66:67], v[134:135]
	v_pk_add_f32 v[64:65], v[64:65], v[132:133]
	s_waitcnt vmcnt(14)
	v_pk_add_f32 v[62:63], v[62:63], v[140:141]
	v_pk_add_f32 v[60:61], v[60:61], v[138:139]
	s_waitcnt vmcnt(13)
	v_pk_add_f32 v[50:51], v[50:51], v[144:145]
	v_pk_add_f32 v[48:49], v[48:49], v[142:143]
	s_waitcnt vmcnt(12)
	v_pk_add_f32 v[46:47], v[46:47], v[148:149]
	v_pk_add_f32 v[44:45], v[44:45], v[146:147]
	s_waitcnt vmcnt(11)
	v_pk_add_f32 v[34:35], v[34:35], v[152:153]
	v_pk_add_f32 v[32:33], v[32:33], v[150:151]
	s_waitcnt vmcnt(10)
	v_pk_add_f32 v[30:31], v[30:31], v[156:157]
	v_pk_add_f32 v[28:29], v[28:29], v[154:155]
	s_waitcnt vmcnt(9)
	v_pk_add_f32 v[18:19], v[18:19], v[160:161]
	v_pk_add_f32 v[16:17], v[16:17], v[158:159]
	s_waitcnt vmcnt(8)
	v_pk_add_f32 v[14:15], v[14:15], v[164:165]
	v_pk_add_f32 v[12:13], v[12:13], v[162:163]
	s_waitcnt vmcnt(7)
	v_pk_add_f32 v[58:59], v[58:59], v[168:169]
	v_pk_add_f32 v[56:57], v[56:57], v[166:167]
	s_waitcnt vmcnt(6)
	v_pk_add_f32 v[54:55], v[54:55], v[172:173]
	v_pk_add_f32 v[52:53], v[52:53], v[170:171]
	s_waitcnt vmcnt(5)
	v_pk_add_f32 v[42:43], v[42:43], v[176:177]
	v_pk_add_f32 v[40:41], v[40:41], v[174:175]
	s_waitcnt vmcnt(4)
	v_pk_add_f32 v[38:39], v[38:39], v[180:181]
	v_pk_add_f32 v[36:37], v[36:37], v[178:179]
	s_waitcnt vmcnt(3)
	v_pk_add_f32 v[26:27], v[26:27], v[184:185]
	v_pk_add_f32 v[24:25], v[24:25], v[182:183]
	s_waitcnt vmcnt(2)
	v_pk_add_f32 v[22:23], v[22:23], v[188:189]
	v_pk_add_f32 v[20:21], v[20:21], v[186:187]
	s_waitcnt vmcnt(1)
	v_pk_add_f32 v[10:11], v[10:11], v[192:193]
	v_pk_add_f32 v[8:9], v[8:9], v[190:191]
	s_waitcnt vmcnt(0)
	v_pk_add_f32 v[6:7], v[6:7], v[196:197]
	v_pk_add_f32 v[4:5], v[4:5], v[194:195]
	s_cbranch_scc1 .LBB0_647
; __device__ __forceinline__ unsigned cvt_pk_bf16(float lo, float hi) { unsigned r; asm volatile("v_cvt_pk_bf16_f32 %0, %1, %2" : "=v"(r) : "v"(lo), "v"(hi)); return r; }
;     __device__ __forceinline__ void operator()(f32x4 (&acc)[2][2][4][2], const Unit& u, int wr, int wc, int fr, int fq) const {
;     ...
;                     u32x4 t[2][2];
; #pragma unroll
;                     for (int mm = 0; mm < 2; ++mm) { const bf16_t* rowp = XB + (size_t)(row0 + ai * HALF + (2 * mp + mm) * 16) * ldc + col0;
; #pragma unroll
;                         for (int bj = 0; bj < 2; ++bj) t[mm][bj] = *(const u32x4*)(rowp + bj * HALF); }
; #pragma unroll
;                     for (int mm = 0; mm < 2; ++mm)
; #pragma unroll
;                         for (int bj = 0; bj < 2; ++bj) { const u32x4 w = t[mm][bj];
;                             acc[ai][bj][2 * mp + mm][0] = acc[ai][bj][2 * mp + mm][0] + (f32x4){__builtin_bit_cast(float, w.x << 16), __builtin_bit_cast(float, w.x & 0xffff0000u), __builtin_bit_cast(float, w.y << 16), __builtin_bit_cast(float, w.y & 0xffff0000u)};
;                             acc[ai][bj][2 * mp + mm][1] = acc[ai][bj][2 * mp + mm][1] + (f32x4){__builtin_bit_cast(float, w.z << 16), __builtin_bit_cast(float, w.z & 0xffff0000u), __builtin_bit_cast(float, w.w << 16), __builtin_bit_cast(float, w.w & 0xffff0000u)}; }
;                 }
; #pragma unroll
;                 for (int mm = 0; mm < 2; ++mm) { const int m = 2 * mp + mm; const int row = row0 + ai * HALF + m * 16; float sq = 0.f;
; #pragma unroll
;                     for (int bj = 0; bj < 2; ++bj) { const f32x4 v0 = acc[ai][bj][m][0], v1 = acc[ai][bj][m][1];
;                         sq += ((v0[0] * v0[0] + v0[1] * v0[1]) + (v0[2] * v0[2] + v0[3] * v0[3])) + ((v1[0] * v1[0] + v1[1] * v1[1]) + (v1[2] * v1[2] + v1[3] * v1[3]));
;                         if (!Y) { u32x4 w; w.x = cvt_pk_bf16(v0[0], v0[1]); w.y = cvt_pk_bf16(v0[2], v0[3]); w.z = cvt_pk_bf16(v1[0], v1[1]); w.w = cvt_pk_bf16(v1[2], v1[3]);
;                             *(u32x4*)(XB + (size_t)row * ldc + col0 + bj * HALF) = w; } }
;                     sq += __shfl_xor(sq, 16); sq += __shfl_xor(sq, 32); if (fq == 0) atomicAdd(ssq + row, sq); }
	v_lshlrev_b32_e32 v0, 3, v137
	v_lshl_or_b32 v0, s1, 5, v0
	v_lshl_or_b32 v0, s6, 8, v0
	v_lshl_add_u32 v144, s0, 8, v136
	v_ashrrev_i32_e32 v1, 31, v0
	v_lshlrev_b64 v[156:157], 1, v[0:1]
	v_ashrrev_i32_e32 v145, 31, v144
	v_lshl_add_u64 v[140:141], s[74:75], 0, v[156:157]
	v_lshlrev_b64 v[142:143], 11, v[144:145]
	v_lshl_add_u64 v[132:133], v[140:141], 0, v[142:143]
	global_load_dwordx4 v[148:151], v[132:133], off
	global_load_dwordx4 v[152:155], v[132:133], off offset:256
	v_or_b32_e32 v132, 16, v144
	v_ashrrev_i32_e32 v133, 31, v132
	v_lshlrev_b64 v[146:147], 11, v[132:133]
	v_lshl_add_u64 v[132:133], v[140:141], 0, v[146:147]
	v_cmp_eq_u32_e32 vcc, 0, v137
	global_load_dwordx4 v[136:139], v[132:133], off
	s_nop 0
	global_load_dwordx4 v[132:135], v[132:133], off offset:256
	s_movk_i32 s2, 0x2000
	s_waitcnt vmcnt(3)
	v_lshlrev_b32_e32 v158, 16, v148
	v_and_b32_e32 v159, 0xffff0000, v148
	v_lshlrev_b32_e32 v148, 16, v149
	v_and_b32_e32 v149, 0xffff0000, v149
	v_pk_add_f32 v[130:131], v[130:131], v[148:149]
	v_lshlrev_b32_e32 v148, 16, v150
	v_and_b32_e32 v149, 0xffff0000, v150
	v_pk_add_f32 v[124:125], v[124:125], v[148:149]
	s_waitcnt vmcnt(2)
	v_lshlrev_b32_e32 v148, 16, v152
	v_and_b32_e32 v149, 0xffff0000, v152
	v_pk_add_f32 v[128:129], v[128:129], v[158:159]
	v_pk_add_f32 v[120:121], v[120:121], v[148:149]
	v_lshlrev_b32_e32 v148, 16, v154
	v_and_b32_e32 v149, 0xffff0000, v154
	v_lshlrev_b32_e32 v150, 16, v151
	v_and_b32_e32 v151, 0xffff0000, v151
	v_pk_add_f32 v[148:149], v[116:117], v[148:149]
	v_mul_f32_e32 v2, v129, v129
	v_mul_f32_e32 v116, v131, v131
	v_pk_add_f32 v[126:127], v[126:127], v[150:151]
	v_fmac_f32_e32 v2, v128, v128
	v_fmac_f32_e32 v116, v130, v130
	v_add_f32_e32 v2, v2, v116
	v_mul_f32_e32 v116, v125, v125
	v_mul_f32_e32 v117, v127, v127
	v_lshlrev_b32_e32 v150, 16, v153
	v_and_b32_e32 v151, 0xffff0000, v153
	v_fmac_f32_e32 v116, v124, v124
	v_fmac_f32_e32 v117, v126, v126
	v_pk_add_f32 v[122:123], v[122:123], v[150:151]
	v_lshlrev_b32_e32 v150, 16, v155
	v_and_b32_e32 v151, 0xffff0000, v155
	v_add_f32_e32 v116, v116, v117
	v_pk_add_f32 v[150:151], v[118:119], v[150:151]
	v_add_f32_e32 v2, v116, v2
	v_cvt_pk_bf16_f32 v116, v128, v129
	v_cvt_pk_bf16_f32 v117, v130, v131
	v_cvt_pk_bf16_f32 v118, v124, v125
	v_lshl_add_u64 v[124:125], s[74:75], 0, v[142:143]
	v_lshl_add_u64 v[124:125], v[124:125], 0, v[156:157]
	v_cvt_pk_bf16_f32 v119, v126, v127
	global_store_dwordx4 v[124:125], v[116:119], off
	s_nop 1
	v_mul_f32_e32 v116, v121, v121
	v_mul_f32_e32 v117, v123, v123
	v_fmac_f32_e32 v116, v120, v120
	v_fmac_f32_e32 v117, v122, v122
	v_add_f32_e32 v116, v116, v117
	v_mul_f32_e32 v117, v149, v149
	v_mul_f32_e32 v118, v151, v151
	v_fmac_f32_e32 v117, v148, v148
	v_fmac_f32_e32 v118, v150, v150
	v_add_f32_e32 v117, v117, v118
	v_add_f32_e32 v116, v117, v116
	v_add_f32_e32 v126, v2, v116
	v_cvt_pk_bf16_f32 v116, v120, v121
	v_cvt_pk_bf16_f32 v117, v122, v123
	v_cvt_pk_bf16_f32 v118, v148, v149
	v_cvt_pk_bf16_f32 v119, v150, v151
	global_store_dwordx4 v[124:125], v[116:119], off offset:256
	v_xor_b32_e32 v2, 16, v215
	s_nop 0
	v_and_b32_e32 v116, 64, v215
	v_add_u32_e32 v116, 64, v116
	v_cmp_lt_i32_e64 s[0:1], v2, v116
	s_nop 1
	v_cndmask_b32_e64 v2, v215, v2, s[0:1]
	v_lshlrev_b32_e32 v2, 2, v2
	ds_bpermute_b32 v117, v2, v126
	s_waitcnt lgkmcnt(0)
	v_add_f32_e32 v119, v126, v117
	v_xor_b32_e32 v117, 32, v215
	v_cmp_lt_i32_e64 s[0:1], v117, v116
	s_nop 1
	v_cndmask_b32_e64 v116, v215, v117, s[0:1]
	v_lshlrev_b32_e32 v118, 2, v116
	ds_bpermute_b32 v120, v118, v119
	v_lshl_add_u64 v[116:117], v[144:145], 2, s[10:11]
	s_and_saveexec_b64 s[0:1], vcc
	s_cbranch_execz .LBB0_650
	s_waitcnt lgkmcnt(0)
	v_add_f32_e32 v119, v119, v120
	global_atomic_add_f32 v[116:117], v119, off
